# added: diff-attn component-1 epilogue reads O1 row-contiguous (combine y - lam*x in LDS, then per-lane f32 sum of squares), on top of o3
# baseline (speedup 1.0000x reference)
; #define SBAR() __builtin_amdgcn_sched_barrier(0)
; #define PV_READ(S, D0) do { S##0 = tr_read<v_rd_off(D0, 0, 0)>(vb); S##1 = tr_read<v_rd_off(D0, 0, 1)>(vb); S##2 = tr_read<v_rd_off(D0, 1, 0)>(vb); S##3 = tr_read<v_rd_off(D0, 1, 1)>(vb); \
;     S##4 = tr_read<v_rd_off(D0, 2, 0)>(vb); S##5 = tr_read<v_rd_off(D0, 2, 1)>(vb); S##6 = tr_read<v_rd_off(D0, 3, 0)>(vb); S##7 = tr_read<v_rd_off(D0, 3, 1)>(vb); } while (0)
; #define PV_MMA(OD, S) do { OD = __builtin_amdgcn_mfma_f32_32x32x16_bf16(pa0, PV_PK(S##0, S##1), OD, 0, 0, 0); OD = __builtin_amdgcn_mfma_f32_32x32x16_bf16(pa1, PV_PK(S##2, S##3), OD, 0, 0, 0); \
;     OD = __builtin_amdgcn_mfma_f32_32x32x16_bf16(pa2, PV_PK(S##4, S##5), OD, 0, 0, 0); OD = __builtin_amdgcn_mfma_f32_32x32x16_bf16(pa3, PV_PK(S##6, S##7), OD, 0, 0, 0); } while (0)
; #define PV_WAIT() do { asm volatile("s_waitcnt lgkmcnt(0)" ::: "memory"); SBAR(); } while (0)
; __device__ __forceinline__ void finishSM(f32x16& p0, f32x16& p1, float alpha, float& l_reg, bf16x8& pa0, bf16x8& pa1, bf16x8& pa2, bf16x8& pa3) {
; #pragma unroll
;   for (int r = 0; r < 16; ++r) p1[r] = __builtin_amdgcn_exp2f(p1[r]);
;   float ps = 0;
; #pragma unroll
;   for (int r = 0; r < 16; ++r) ps += p0[r];
; #pragma unroll
;   for (int r = 0; r < 16; ++r) ps += p1[r];
;   { auto rr = __builtin_amdgcn_permlane32_swap(__float_as_uint(ps), __float_as_uint(ps), false, false);
;     ps = __uint_as_float(rr[0]) + __uint_as_float(rr[1]); }
;   l_reg = l_reg * alpha + ps;
;     ...
;   PK4(p0, 0, pa0); PK4(p0, 8, pa1); PK4(p1, 0, pa2); PK4(p1, 8, pa3);
; __device__ __forceinline__ void pv_pipe(f32x16* o, int vb, bf16x8 pa0, bf16x8 pa1, bf16x8 pa2, bf16x8 pa3) {
;   s16x4 a0, a1, a2, a3, a4, a5, a6, a7, b0, b1, b2, b3, b4, b5, b6, b7;
;   PV_READ(a, 0); PV_WAIT();
;   PV_READ(b, 1); SBAR(); PV_MMA(o[0], a); PV_WAIT();
;   PV_READ(a, 2); SBAR(); PV_MMA(o[1], b); PV_WAIT();
;   PV_READ(b, 3); SBAR(); PV_MMA(o[2], a); PV_WAIT();
;   PV_MMA(o[3], b);
; }
.LBB0_777:
	v_exp_f32_e32 v82, v98
	v_exp_f32_e32 v83, v99
	v_exp_f32_e32 v84, v100
	v_exp_f32_e32 v85, v101
	v_exp_f32_e32 v86, v102
	v_exp_f32_e32 v98, v66
	v_add_f32_e32 v66, 0, v82
	v_exp_f32_e32 v87, v103
	v_add_f32_e32 v66, v83, v66
	v_exp_f32_e32 v88, v104
	v_add_f32_e32 v66, v84, v66
	v_exp_f32_e32 v89, v105
	v_add_f32_e32 v66, v85, v66
	v_exp_f32_e32 v90, v106
	v_add_f32_e32 v66, v86, v66
	v_exp_f32_e32 v91, v107
	v_add_f32_e32 v66, v87, v66
	v_exp_f32_e32 v92, v108
	v_add_f32_e32 v66, v88, v66
	v_exp_f32_e32 v93, v109
	v_add_f32_e32 v66, v89, v66
	v_exp_f32_e32 v94, v110
	v_add_f32_e32 v66, v90, v66
	v_exp_f32_e32 v95, v111
	v_add_f32_e32 v66, v91, v66
	v_exp_f32_e32 v96, v112
	v_add_f32_e32 v66, v92, v66
	v_exp_f32_e32 v97, v113
	v_add_f32_e32 v66, v93, v66
	v_add_f32_e32 v66, v94, v66
	v_exp_f32_e32 v99, v67
	v_add_f32_e32 v66, v95, v66
	v_exp_f32_e32 v100, v68
	v_add_f32_e32 v66, v96, v66
	v_exp_f32_e32 v101, v69
	v_add_f32_e32 v66, v97, v66
	v_exp_f32_e32 v102, v70
	v_add_f32_e32 v66, v98, v66
	v_exp_f32_e32 v103, v71
	v_add_f32_e32 v66, v99, v66
	v_exp_f32_e32 v104, v72
	v_add_f32_e32 v66, v100, v66
	v_exp_f32_e32 v105, v73
	v_add_f32_e32 v66, v101, v66
	v_exp_f32_e32 v106, v74
	v_add_f32_e32 v66, v102, v66
	v_exp_f32_e32 v107, v75
	v_add_f32_e32 v66, v103, v66
	v_exp_f32_e32 v108, v76
	v_add_f32_e32 v66, v104, v66
	v_exp_f32_e32 v109, v77
	v_add_f32_e32 v66, v105, v66
	v_exp_f32_e32 v110, v78
	v_add_f32_e32 v66, v106, v66
	v_exp_f32_e32 v111, v79
	v_add_f32_e32 v66, v107, v66
	v_exp_f32_e32 v112, v80
	v_add_f32_e32 v66, v108, v66
	v_exp_f32_e32 v113, v81
	v_add_f32_e32 v66, v109, v66
	v_add_f32_e32 v66, v110, v66
	v_add_f32_e32 v66, v111, v66
	v_add_f32_e32 v66, v112, v66
	v_add_f32_e32 v66, v113, v66
	v_mov_b32_e32 v67, v66
	s_nop 1
	v_permlane32_swap_b32_e32 v66, v67
	v_cvt_pk_bf16_f32 v68, v82, v83
	v_cvt_pk_bf16_f32 v69, v84, v85
	v_cvt_pk_bf16_f32 v70, v86, v87
	v_cvt_pk_bf16_f32 v71, v88, v89
	v_cvt_pk_bf16_f32 v72, v90, v91
	v_cvt_pk_bf16_f32 v73, v92, v93
	v_cvt_pk_bf16_f32 v74, v94, v95
	v_cvt_pk_bf16_f32 v75, v96, v97
	v_cvt_pk_bf16_f32 v76, v98, v99
	v_cvt_pk_bf16_f32 v77, v100, v101
	v_cvt_pk_bf16_f32 v78, v102, v103
	v_cvt_pk_bf16_f32 v79, v104, v105
	v_cvt_pk_bf16_f32 v80, v106, v107
	v_cvt_pk_bf16_f32 v81, v108, v109
	v_cvt_pk_bf16_f32 v82, v110, v111
	v_cvt_pk_bf16_f32 v83, v112, v113
	v_permlane32_swap_b32_e32 v68, v70
	v_permlane32_swap_b32_e32 v69, v71
	v_permlane32_swap_b32_e32 v72, v74
	v_permlane32_swap_b32_e32 v73, v75
	v_permlane32_swap_b32_e32 v76, v78
	v_permlane32_swap_b32_e32 v77, v79
	v_permlane32_swap_b32_e32 v80, v82
	v_permlane32_swap_b32_e32 v81, v83
	ds_read_b64_tr_b16 v[84:85], v173 offset:0
	ds_read_b64_tr_b16 v[86:87], v173 offset:0x800
	ds_read_b64_tr_b16 v[88:89], v173 offset:0x1000
	ds_read_b64_tr_b16 v[90:91], v173 offset:0x1800
	ds_read_b64_tr_b16 v[92:93], v173 offset:0x2000
	ds_read_b64_tr_b16 v[94:95], v173 offset:0x2800
	ds_read_b64_tr_b16 v[96:97], v173 offset:0x3000
	ds_read_b64_tr_b16 v[98:99], v173 offset:0x3800
	s_waitcnt lgkmcnt(0)
	ds_read_b64_tr_b16 v[100:101], v173 offset:0x200
	ds_read_b64_tr_b16 v[102:103], v173 offset:0xa00
	ds_read_b64_tr_b16 v[104:105], v173 offset:0x1200
	ds_read_b64_tr_b16 v[106:107], v173 offset:0x1a00
	ds_read_b64_tr_b16 v[108:109], v173 offset:0x2200
	ds_read_b64_tr_b16 v[110:111], v173 offset:0x2a00
	ds_read_b64_tr_b16 v[118:119], v173 offset:0x3200
	ds_read_b64_tr_b16 v[120:121], v173 offset:0x3a00
	s_nop 0
	v_mfma_f32_32x32x16_bf16 v[2:17], v[68:71], v[84:87], v[2:17]
	s_waitcnt lgkmcnt(0)
	v_mfma_f32_32x32x16_bf16 v[2:17], v[72:75], v[88:91], v[2:17]
	v_mfma_f32_32x32x16_bf16 v[2:17], v[76:79], v[92:95], v[2:17]
	v_mfma_f32_32x32x16_bf16 v[2:17], v[80:83], v[96:99], v[2:17]
	ds_read_b64_tr_b16 v[84:85], v173 offset:0x400
	ds_read_b64_tr_b16 v[86:87], v173 offset:0xc00
	ds_read_b64_tr_b16 v[88:89], v173 offset:0x1400
	ds_read_b64_tr_b16 v[90:91], v173 offset:0x1c00
	ds_read_b64_tr_b16 v[92:93], v173 offset:0x2400
	ds_read_b64_tr_b16 v[94:95], v173 offset:0x2c00
	ds_read_b64_tr_b16 v[96:97], v173 offset:0x3400
	ds_read_b64_tr_b16 v[98:99], v173 offset:0x3c00
	v_mfma_f32_32x32x16_bf16 v[50:65], v[68:71], v[100:103], v[50:65]
	s_waitcnt lgkmcnt(0)
	v_mfma_f32_32x32x16_bf16 v[50:65], v[72:75], v[104:107], v[50:65]
	v_mfma_f32_32x32x16_bf16 v[50:65], v[76:79], v[108:111], v[50:65]
	v_mfma_f32_32x32x16_bf16 v[50:65], v[80:83], v[118:121], v[50:65]
	ds_read_b64_tr_b16 v[100:101], v173 offset:0x600
	ds_read_b64_tr_b16 v[102:103], v173 offset:0xe00
	ds_read_b64_tr_b16 v[104:105], v173 offset:0x1600
	ds_read_b64_tr_b16 v[106:107], v173 offset:0x1e00
	ds_read_b64_tr_b16 v[108:109], v173 offset:0x2600
	ds_read_b64_tr_b16 v[110:111], v173 offset:0x2e00
	ds_read_b64_tr_b16 v[118:119], v173 offset:0x3600
	ds_read_b64_tr_b16 v[120:121], v173 offset:0x3e00
	v_mfma_f32_32x32x16_bf16 v[34:49], v[68:71], v[84:87], v[34:49]
	s_waitcnt lgkmcnt(0)
	v_mfma_f32_32x32x16_bf16 v[34:49], v[72:75], v[88:91], v[34:49]
	v_mfma_f32_32x32x16_bf16 v[34:49], v[76:79], v[92:95], v[34:49]
	v_mfma_f32_32x32x16_bf16 v[34:49], v[80:83], v[96:99], v[34:49]
	v_mfma_f32_32x32x16_bf16 v[18:33], v[68:71], v[100:103], v[18:33]
	v_mfma_f32_32x32x16_bf16 v[18:33], v[72:75], v[104:107], v[18:33]
	v_mfma_f32_32x32x16_bf16 v[18:33], v[76:79], v[108:111], v[18:33]
	v_mfma_f32_32x32x16_bf16 v[18:33], v[80:83], v[118:121], v[18:33]
	s_and_saveexec_b64 s[8:9], s[38:39]
	v_add_f32_e32 v68, v114, v115
	v_fmac_f32_e32 v68, v193, v180
	v_add_f32_e32 v66, v66, v67
	v_fmac_f32_e32 v66, v68, v116
	ds_write_b32 v192, v66
	s_or_b64 exec, exec, s[8:9]
	s_waitcnt lgkmcnt(0)
	v_add_u32_e32 v74, s31, v160
	ds_read_b128 v[66:69], v74
	ds_read_b128 v[70:73], v74 offset:32
	s_and_b32 s10, s28, 0xf00
	s_lshl_b32 s11, s30, 9
	s_add_u32 s0, s10, s0
	s_waitcnt lgkmcnt(1)
	v_rcp_f32_e32 v75, v66
	v_rcp_f32_e32 v76, v67
	v_rcp_f32_e32 v77, v68
	v_rcp_f32_e32 v78, v69
	ds_read_b128 v[66:69], v74 offset:64
	s_waitcnt lgkmcnt(1)
	v_rcp_f32_e32 v79, v70
	v_rcp_f32_e32 v80, v71
	v_rcp_f32_e32 v81, v72
	v_rcp_f32_e32 v82, v73
	ds_read_b128 v[70:73], v74 offset:96
	s_waitcnt lgkmcnt(1)
	v_rcp_f32_e32 v74, v66
	v_mov_b32_e32 v66, v186
	s_waitcnt lgkmcnt(0)
	s_barrier
; __device__ __forceinline__ u32x4 pack8(const f32x4 a, const f32x4 b) { u32x4 w; w.x = cvt_pk(a[0], a[1]); w.y = cvt_pk(a[2], a[3]); w.z = cvt_pk(b[0], b[1]); w.w = cvt_pk(b[2], b[3]); return w; }
; __device__ __forceinline__ float sq4(f32x4 v) { return (v[0] * v[0] + v[1] * v[1]) + (v[2] * v[2] + v[3] * v[3]); }
; __device__ __forceinline__ int crow(int r, int hi) { return (r & 3) + 8 * (r >> 2) + 4 * hi; }
; __device__ __forceinline__ int opaque_tid() { int t = threadIdx.x; asm volatile("" : "+v"(t)); return t; }
; template <int MODE> __device__ __forceinline__ void attn_epilogue(char* lds, const att::f32x16 (&o)[4], const float (&rli)[16], float* o1, bf16raw* ob, float lam, float post, const float* gs) {
;     const int tid_ = opaque_tid(); const int lane = tid_ & 63, wave = tid_ >> 6, r32 = lane & 31, hi = lane >> 5;
;     float* st = (float*)(lds + wave * ATT_STAGE);
; #pragma unroll
;     for (int r = 0; r < 16; ++r) { const int orow = att::crow(r, hi);
; #pragma unroll
;         for (int d0 = 0; d0 < 4; ++d0) st[orow * 132 + d0 * 32 + r32] = o[d0][r] * rli[r]; }
;     asm volatile("s_waitcnt lgkmcnt(0)" ::: "memory");
;     float* sr = st + r32 * 132 + 64 * hi;
;     const size_t goff = (size_t)r32 * 1024 + 64 * hi, boff = (size_t)r32 * 2048 + 64 * hi;
;     if constexpr (MODE == 0) {
; #pragma unroll 4
;         for (int j = 0; j < 16; ++j) *(f32x4*)(o1 + goff + 4 * j) = *(const f32x4*)(sr + 4 * j);
;     } else if constexpr (MODE == 2) {
; #pragma unroll 4
;         for (int j = 0; j < 8; ++j) *(ep::u32x4*)(ob + boff + 8 * j) = ep::pack8(*(const f32x4*)(sr + 8 * j), *(const f32x4*)(sr + 8 * j + 4));
;     } else {
;         float s = 0.f;
; #pragma unroll 4
;         for (int j = 0; j < 16; ++j) { const f32x4 x = *(const f32x4*)(sr + 4 * j), y = *(const f32x4*)(o1 + goff + 4 * j); const f32x4 v = y - x * lam; s += ep::sq4(v); *(f32x4*)(sr + 4 * j) = v; }
	v_rcp_f32_e32 v83, v67
	ds_read_b64 v[66:67], v66 offset:72
	v_mul_f32_e32 v2, v2, v75
	v_mul_f32_e32 v50, v50, v75
	v_mul_f32_e32 v18, v18, v75
	v_rcp_f32_e32 v68, v68
	s_waitcnt lgkmcnt(0)
	v_readfirstlane_b32 s9, v66
	v_mov_b32_e32 v66, v0
	v_readfirstlane_b32 s8, v67
	v_rcp_f32_e32 v69, v69
	v_lshrrev_b32_e32 v67, 6, v66
	v_and_b32_e32 v84, 31, v66
	v_bfe_u32 v66, v66, 5, 1
	v_mul_lo_u32 v67, v67, s75
	v_add_u32_e32 v67, 0, v67
	v_lshlrev_b32_e32 v85, 2, v84
	v_mul_u32_u24_e32 v86, 0x840, v66
	v_add3_u32 v85, v67, v85, v86
	ds_write2_b32 v85, v2, v50 offset1:32
	v_mul_f32_e32 v2, v34, v75
	ds_write2_b32 v85, v2, v18 offset0:64 offset1:96
	v_mul_f32_e32 v2, v3, v76
	v_mul_f32_e32 v3, v51, v76
	ds_write2_b32 v85, v2, v3 offset0:132 offset1:164
	v_mul_f32_e32 v2, v35, v76
	v_mul_f32_e32 v3, v19, v76
	ds_write2_b32 v85, v2, v3 offset0:196 offset1:228
	v_mul_f32_e32 v2, v4, v77
	v_mul_f32_e32 v3, v52, v77
	v_add_u32_e32 v4, 0x400, v85
	ds_write2_b32 v4, v2, v3 offset0:8 offset1:40
	v_mul_f32_e32 v2, v36, v77
	v_mul_f32_e32 v3, v20, v77
	ds_write2_b32 v4, v2, v3 offset0:72 offset1:104
	v_mul_f32_e32 v2, v5, v78
	v_mul_f32_e32 v3, v53, v78
	ds_write2_b32 v4, v2, v3 offset0:140 offset1:172
	v_mul_f32_e32 v2, v37, v78
	v_mul_f32_e32 v3, v21, v78
	ds_write2_b32 v4, v2, v3 offset0:204 offset1:236
	v_mul_f32_e32 v2, v6, v79
	v_mul_f32_e32 v3, v54, v79
	v_add_u32_e32 v4, 0x1000, v85
	ds_write2_b32 v4, v2, v3 offset0:32 offset1:64
	v_mul_f32_e32 v2, v38, v79
	v_mul_f32_e32 v3, v22, v79
	ds_write2_b32 v4, v2, v3 offset0:96 offset1:128
	v_mul_f32_e32 v2, v7, v80
	v_mul_f32_e32 v3, v55, v80
	ds_write2_b32 v4, v2, v3 offset0:164 offset1:196
	v_mul_f32_e32 v2, v39, v80
	v_mul_f32_e32 v3, v23, v80
	v_add_u32_e32 v4, 0x1200, v85
	ds_write2_b32 v4, v2, v3 offset0:100 offset1:132
	v_mul_f32_e32 v2, v8, v81
	v_mul_f32_e32 v3, v56, v81
	v_add_u32_e32 v4, 0x1400, v85
	ds_write2_b32 v4, v2, v3 offset0:40 offset1:72
	v_mul_f32_e32 v2, v40, v81
	v_mul_f32_e32 v3, v24, v81
	ds_write2_b32 v4, v2, v3 offset0:104 offset1:136
	v_mul_f32_e32 v2, v9, v82
	v_mul_f32_e32 v3, v57, v82
	ds_write2_b32 v4, v2, v3 offset0:172 offset1:204
	v_mul_f32_e32 v2, v41, v82
	v_mul_f32_e32 v3, v25, v82
	v_add_u32_e32 v4, 0x1600, v85
	ds_write2_b32 v4, v2, v3 offset0:108 offset1:140
	v_mul_f32_e32 v2, v10, v74
	v_mul_f32_e32 v3, v58, v74
	v_add_u32_e32 v4, 0x2000, v85
	ds_write2_b32 v4, v2, v3 offset0:64 offset1:96
	v_mul_f32_e32 v2, v42, v74
	v_mul_f32_e32 v3, v26, v74
	ds_write2_b32 v4, v2, v3 offset0:128 offset1:160
	v_mul_f32_e32 v2, v11, v83
	v_mul_f32_e32 v3, v59, v83
	ds_write2_b32 v4, v2, v3 offset0:196 offset1:228
	v_mul_f32_e32 v2, v43, v83
	v_mul_f32_e32 v3, v27, v83
	v_add_u32_e32 v4, 0x2400, v85
	v_rcp_f32_e32 v70, v70
	ds_write2_b32 v4, v2, v3 offset0:4 offset1:36
	v_mul_f32_e32 v2, v12, v68
	v_mul_f32_e32 v3, v60, v68
	ds_write2_b32 v4, v2, v3 offset0:72 offset1:104
	v_mul_f32_e32 v2, v44, v68
	v_mul_f32_e32 v3, v28, v68
	v_rcp_f32_e32 v71, v71
	ds_write2_b32 v4, v2, v3 offset0:136 offset1:168
	v_mul_f32_e32 v2, v13, v69
	v_mul_f32_e32 v3, v61, v69
	ds_write2_b32 v4, v2, v3 offset0:204 offset1:236
	v_mul_f32_e32 v2, v45, v69
	v_mul_f32_e32 v3, v29, v69
	v_add_u32_e32 v4, 0x2800, v85
	v_rcp_f32_e32 v72, v72
	ds_write2_b32 v4, v2, v3 offset0:12 offset1:44
	v_mul_f32_e32 v2, v14, v70
	v_mul_f32_e32 v3, v62, v70
	v_add_u32_e32 v4, 0x3000, v85
	ds_write2_b32 v4, v2, v3 offset0:96 offset1:128
	v_mul_f32_e32 v2, v46, v70
	v_mul_f32_e32 v3, v30, v70
	v_rcp_f32_e32 v73, v73
	ds_write2_b32 v4, v2, v3 offset0:160 offset1:192
	v_mul_f32_e32 v2, v15, v71
	v_mul_f32_e32 v3, v63, v71
	v_add_u32_e32 v4, 0x3200, v85
	ds_write2_b32 v4, v2, v3 offset0:100 offset1:132
	v_mul_f32_e32 v2, v47, v71
	v_mul_f32_e32 v3, v31, v71
	v_add_u32_e32 v4, 0x3400, v85
	ds_write2_b32 v4, v2, v3 offset0:36 offset1:68
	v_mul_f32_e32 v2, v16, v72
	v_mul_f32_e32 v3, v64, v72
	ds_write2_b32 v4, v2, v3 offset0:104 offset1:136
	v_mul_f32_e32 v2, v48, v72
	v_mul_f32_e32 v3, v32, v72
	ds_write2_b32 v4, v2, v3 offset0:168 offset1:200
	v_mul_f32_e32 v2, v17, v73
	v_mul_f32_e32 v3, v65, v73
	v_add_u32_e32 v4, 0x3600, v85
	ds_write2_b32 v4, v2, v3 offset0:108 offset1:140
	v_mul_f32_e32 v2, v49, v73
	v_mul_f32_e32 v3, v33, v73
	v_add_u32_e32 v4, 0x3800, v85
	ds_write2_b32 v4, v2, v3 offset0:44 offset1:76
	v_mul_u32_u24_e32 v2, 0x210, v84
	v_lshlrev_b32_e32 v4, 8, v66
	s_addc_u32 s1, 0, s1
	v_add3_u32 v10, v67, v2, v4
	v_lshl_add_u64 v[2:3], s[0:1], 0, v[170:171]
	v_lshlrev_b32_e32 v160, 12, v84
	v_lshlrev_b64 v[2:3], 12, v[2:3]
	s_waitcnt lgkmcnt(0)
	v_lshl_add_u64 v[2:3], v[2:3], 0, v[160:161]
	v_or3_b32 v4, v2, s11, v4
	v_mov_b32_e32 v5, v3
	v_lshlrev_b32_e32 v6, 6, v66
	v_lshl_add_u64 v[4:5], s[14:15], 0, v[4:5]
	v_mov_b32_e32 v7, 0
	v_lshlrev_b32_e32 v244, 12, v84
	v_lshl_add_u32 v244, v66, 8, v244
	v_sub_co_u32_e32 v4, vcc, v4, v244
	s_nop 1
	v_subbrev_co_u32_e32 v5, vcc, 0, v5, vcc
	v_lshlrev_b32_e32 v244, 12, v66
	v_lshl_add_u32 v244, v84, 4, v244
	v_mov_b32_e32 v245, 0
	v_lshl_add_u64 v[4:5], v[4:5], 0, v[244:245]
	v_mul_u32_u24_e32 v253, 0x210, v66
	v_lshl_add_u32 v253, v84, 4, v253
	v_add_u32_e32 v253, v67, v253
	s_mov_b32 s98, 0x2000
	s_mov_b32 s99, 0
	global_load_dwordx4 v[12:15], v[4:5], off offset:-32
	v_lshl_add_u64 v[4:5], v[4:5], 0, s[98:99]
	ds_read_b128 v[28:31], v253
	global_load_dwordx4 v[16:19], v[4:5], off offset:-32
	v_lshl_add_u64 v[4:5], v[4:5], 0, s[98:99]
	ds_read_b128 v[32:35], v253 offset:1056
	global_load_dwordx4 v[20:23], v[4:5], off offset:-32
	v_lshl_add_u64 v[4:5], v[4:5], 0, s[98:99]
	ds_read_b128 v[36:39], v253 offset:2112
	global_load_dwordx4 v[24:27], v[4:5], off offset:-32
	v_lshl_add_u64 v[4:5], v[4:5], 0, s[98:99]
	ds_read_b128 v[40:43], v253 offset:3168
	s_waitcnt vmcnt(3) lgkmcnt(3)
; __device__ __forceinline__ float sq4(f32x4 v) { return (v[0] * v[0] + v[1] * v[1]) + (v[2] * v[2] + v[3] * v[3]); }
; template <int MODE> __device__ __forceinline__ void attn_epilogue(char* lds, const att::f32x16 (&o)[4], const float (&rli)[16], float* o1, bf16raw* ob, float lam, float post, const float* gs) {
;     ...
;         for (int j = 0; j < 16; ++j) { const f32x4 x = *(const f32x4*)(sr + 4 * j), y = *(const f32x4*)(o1 + goff + 4 * j); const f32x4 v = y - x * lam; s += ep::sq4(v); *(f32x4*)(sr + 4 * j) = v; }
	v_fma_f32 v12, -v168, v28, v12
	v_fma_f32 v13, -v168, v29, v13
	v_fma_f32 v14, -v168, v30, v14
	v_fma_f32 v15, -v168, v31, v15
	ds_write_b128 v253, v[12:15]
	s_waitcnt vmcnt(2) lgkmcnt(3)
	v_fma_f32 v16, -v168, v32, v16
	v_fma_f32 v17, -v168, v33, v17
	v_fma_f32 v18, -v168, v34, v18
	v_fma_f32 v19, -v168, v35, v19
	ds_write_b128 v253, v[16:19] offset:1056
	s_waitcnt vmcnt(1) lgkmcnt(3)
	v_fma_f32 v20, -v168, v36, v20
	v_fma_f32 v21, -v168, v37, v21
	v_fma_f32 v22, -v168, v38, v22
	v_fma_f32 v23, -v168, v39, v23
	ds_write_b128 v253, v[20:23] offset:2112
	s_waitcnt vmcnt(0) lgkmcnt(3)
	v_fma_f32 v24, -v168, v40, v24
	v_fma_f32 v25, -v168, v41, v25
	v_fma_f32 v26, -v168, v42, v26
	v_fma_f32 v27, -v168, v43, v27
	ds_write_b128 v253, v[24:27] offset:3168
	global_load_dwordx4 v[12:15], v[4:5], off offset:-32
	v_lshl_add_u64 v[4:5], v[4:5], 0, s[98:99]
	ds_read_b128 v[28:31], v253 offset:4224
	global_load_dwordx4 v[16:19], v[4:5], off offset:-32
	v_lshl_add_u64 v[4:5], v[4:5], 0, s[98:99]
	ds_read_b128 v[32:35], v253 offset:5280
	global_load_dwordx4 v[20:23], v[4:5], off offset:-32
	v_lshl_add_u64 v[4:5], v[4:5], 0, s[98:99]
	ds_read_b128 v[36:39], v253 offset:6336
	global_load_dwordx4 v[24:27], v[4:5], off offset:-32
	v_lshl_add_u64 v[4:5], v[4:5], 0, s[98:99]
	ds_read_b128 v[40:43], v253 offset:7392
	s_waitcnt vmcnt(3) lgkmcnt(3)
	v_fma_f32 v12, -v168, v28, v12
	v_fma_f32 v13, -v168, v29, v13
	v_fma_f32 v14, -v168, v30, v14
	v_fma_f32 v15, -v168, v31, v15
	ds_write_b128 v253, v[12:15] offset:4224
	s_waitcnt vmcnt(2) lgkmcnt(3)
	v_fma_f32 v16, -v168, v32, v16
	v_fma_f32 v17, -v168, v33, v17
	v_fma_f32 v18, -v168, v34, v18
	v_fma_f32 v19, -v168, v35, v19
	ds_write_b128 v253, v[16:19] offset:5280
	s_waitcnt vmcnt(1) lgkmcnt(3)
	v_fma_f32 v20, -v168, v36, v20
	v_fma_f32 v21, -v168, v37, v21
	v_fma_f32 v22, -v168, v38, v22
	v_fma_f32 v23, -v168, v39, v23
	ds_write_b128 v253, v[20:23] offset:6336
	s_waitcnt vmcnt(0) lgkmcnt(3)
	v_fma_f32 v24, -v168, v40, v24
	v_fma_f32 v25, -v168, v41, v25
	v_fma_f32 v26, -v168, v42, v26
	v_fma_f32 v27, -v168, v43, v27
	ds_write_b128 v253, v[24:27] offset:7392
	global_load_dwordx4 v[12:15], v[4:5], off offset:-32
	v_lshl_add_u64 v[4:5], v[4:5], 0, s[98:99]
	ds_read_b128 v[28:31], v253 offset:8448
	global_load_dwordx4 v[16:19], v[4:5], off offset:-32
	v_lshl_add_u64 v[4:5], v[4:5], 0, s[98:99]
	ds_read_b128 v[32:35], v253 offset:9504
	global_load_dwordx4 v[20:23], v[4:5], off offset:-32
	v_lshl_add_u64 v[4:5], v[4:5], 0, s[98:99]
	ds_read_b128 v[36:39], v253 offset:10560
	global_load_dwordx4 v[24:27], v[4:5], off offset:-32
	v_lshl_add_u64 v[4:5], v[4:5], 0, s[98:99]
	ds_read_b128 v[40:43], v253 offset:11616
	s_waitcnt vmcnt(3) lgkmcnt(3)
	v_fma_f32 v12, -v168, v28, v12
	v_fma_f32 v13, -v168, v29, v13
	v_fma_f32 v14, -v168, v30, v14
	v_fma_f32 v15, -v168, v31, v15
	ds_write_b128 v253, v[12:15] offset:8448
	s_waitcnt vmcnt(2) lgkmcnt(3)
	v_fma_f32 v16, -v168, v32, v16
	v_fma_f32 v17, -v168, v33, v17
	v_fma_f32 v18, -v168, v34, v18
	v_fma_f32 v19, -v168, v35, v19
	ds_write_b128 v253, v[16:19] offset:9504
	s_waitcnt vmcnt(1) lgkmcnt(3)
	v_fma_f32 v20, -v168, v36, v20
	v_fma_f32 v21, -v168, v37, v21
	v_fma_f32 v22, -v168, v38, v22
	v_fma_f32 v23, -v168, v39, v23
	ds_write_b128 v253, v[20:23] offset:10560
	s_waitcnt vmcnt(0) lgkmcnt(3)
	v_fma_f32 v24, -v168, v40, v24
	v_fma_f32 v25, -v168, v41, v25
	v_fma_f32 v26, -v168, v42, v26
	v_fma_f32 v27, -v168, v43, v27
	ds_write_b128 v253, v[24:27] offset:11616
	global_load_dwordx4 v[12:15], v[4:5], off offset:-32
	v_lshl_add_u64 v[4:5], v[4:5], 0, s[98:99]
	ds_read_b128 v[28:31], v253 offset:12672
	global_load_dwordx4 v[16:19], v[4:5], off offset:-32
	v_lshl_add_u64 v[4:5], v[4:5], 0, s[98:99]
	ds_read_b128 v[32:35], v253 offset:13728
	global_load_dwordx4 v[20:23], v[4:5], off offset:-32
	v_lshl_add_u64 v[4:5], v[4:5], 0, s[98:99]
	ds_read_b128 v[36:39], v253 offset:14784
	global_load_dwordx4 v[24:27], v[4:5], off offset:-32
	v_lshl_add_u64 v[4:5], v[4:5], 0, s[98:99]
	ds_read_b128 v[40:43], v253 offset:15840
	s_waitcnt vmcnt(3) lgkmcnt(3)
	v_fma_f32 v12, -v168, v28, v12
	v_fma_f32 v13, -v168, v29, v13
	v_fma_f32 v14, -v168, v30, v14
	v_fma_f32 v15, -v168, v31, v15
	ds_write_b128 v253, v[12:15] offset:12672
	s_waitcnt vmcnt(2) lgkmcnt(3)
	v_fma_f32 v16, -v168, v32, v16
	v_fma_f32 v17, -v168, v33, v17
	v_fma_f32 v18, -v168, v34, v18
	v_fma_f32 v19, -v168, v35, v19
	ds_write_b128 v253, v[16:19] offset:13728
	s_waitcnt vmcnt(1) lgkmcnt(3)
	v_fma_f32 v20, -v168, v36, v20
	v_fma_f32 v21, -v168, v37, v21
	v_fma_f32 v22, -v168, v38, v22
	v_fma_f32 v23, -v168, v39, v23
	ds_write_b128 v253, v[20:23] offset:14784
	s_waitcnt vmcnt(0) lgkmcnt(3)
; __device__ __forceinline__ float sq4(f32x4 v) { return (v[0] * v[0] + v[1] * v[1]) + (v[2] * v[2] + v[3] * v[3]); }
; template <int MODE> __device__ __forceinline__ void attn_epilogue(char* lds, const att::f32x16 (&o)[4], const float (&rli)[16], float* o1, bf16raw* ob, float lam, float post, const float* gs) {
;     ...
;         for (int j = 0; j < 16; ++j) { const f32x4 x = *(const f32x4*)(sr + 4 * j), y = *(const f32x4*)(o1 + goff + 4 * j); const f32x4 v = y - x * lam; s += ep::sq4(v); *(f32x4*)(sr + 4 * j) = v; }
;         s += __shfl_xor(s, 32);
;         const float rs = post / sqrtf(s * (1.0f / 128.0f) + 1e-5f);
	v_fma_f32 v24, -v168, v40, v24
	v_fma_f32 v25, -v168, v41, v25
	v_fma_f32 v26, -v168, v42, v26
	v_fma_f32 v27, -v168, v43, v27
	ds_write_b128 v253, v[24:27] offset:15840
	s_waitcnt lgkmcnt(0)
	v_mov_b32_e32 v8, 0
	v_mov_b32_e32 v9, 0
	v_mov_b32_e32 v11, 0
	ds_read_b128 v[12:15], v10
	ds_read_b128 v[16:19], v10 offset:16
	ds_read_b128 v[20:23], v10 offset:32
	ds_read_b128 v[24:27], v10 offset:48
	s_waitcnt lgkmcnt(3)
	v_fmac_f32_e32 v7, v12, v12
	v_fmac_f32_e32 v8, v13, v13
	v_fmac_f32_e32 v9, v14, v14
	v_fmac_f32_e32 v11, v15, v15
	s_waitcnt lgkmcnt(2)
	v_fmac_f32_e32 v7, v16, v16
	v_fmac_f32_e32 v8, v17, v17
	v_fmac_f32_e32 v9, v18, v18
	v_fmac_f32_e32 v11, v19, v19
	s_waitcnt lgkmcnt(1)
	v_fmac_f32_e32 v7, v20, v20
	v_fmac_f32_e32 v8, v21, v21
	v_fmac_f32_e32 v9, v22, v22
	v_fmac_f32_e32 v11, v23, v23
	s_waitcnt lgkmcnt(0)
	v_fmac_f32_e32 v7, v24, v24
	v_fmac_f32_e32 v8, v25, v25
	v_fmac_f32_e32 v9, v26, v26
	v_fmac_f32_e32 v11, v27, v27
	ds_read_b128 v[12:15], v10 offset:64
	ds_read_b128 v[16:19], v10 offset:80
	ds_read_b128 v[20:23], v10 offset:96
	ds_read_b128 v[24:27], v10 offset:112
	s_waitcnt lgkmcnt(3)
	v_fmac_f32_e32 v7, v12, v12
	v_fmac_f32_e32 v8, v13, v13
	v_fmac_f32_e32 v9, v14, v14
	v_fmac_f32_e32 v11, v15, v15
	s_waitcnt lgkmcnt(2)
	v_fmac_f32_e32 v7, v16, v16
	v_fmac_f32_e32 v8, v17, v17
	v_fmac_f32_e32 v9, v18, v18
	v_fmac_f32_e32 v11, v19, v19
	s_waitcnt lgkmcnt(1)
	v_fmac_f32_e32 v7, v20, v20
	v_fmac_f32_e32 v8, v21, v21
	v_fmac_f32_e32 v9, v22, v22
	v_fmac_f32_e32 v11, v23, v23
	s_waitcnt lgkmcnt(0)
	v_fmac_f32_e32 v7, v24, v24
	v_fmac_f32_e32 v8, v25, v25
	v_fmac_f32_e32 v9, v26, v26
	v_fmac_f32_e32 v11, v27, v27
	ds_read_b128 v[12:15], v10 offset:128
	ds_read_b128 v[16:19], v10 offset:144
	ds_read_b128 v[20:23], v10 offset:160
	ds_read_b128 v[24:27], v10 offset:176
	s_waitcnt lgkmcnt(3)
	v_fmac_f32_e32 v7, v12, v12
	v_fmac_f32_e32 v8, v13, v13
	v_fmac_f32_e32 v9, v14, v14
	v_fmac_f32_e32 v11, v15, v15
	s_waitcnt lgkmcnt(2)
	v_fmac_f32_e32 v7, v16, v16
	v_fmac_f32_e32 v8, v17, v17
	v_fmac_f32_e32 v9, v18, v18
	v_fmac_f32_e32 v11, v19, v19
	s_waitcnt lgkmcnt(1)
	v_fmac_f32_e32 v7, v20, v20
	v_fmac_f32_e32 v8, v21, v21
	v_fmac_f32_e32 v9, v22, v22
	v_fmac_f32_e32 v11, v23, v23
	s_waitcnt lgkmcnt(0)
	v_fmac_f32_e32 v7, v24, v24
	v_fmac_f32_e32 v8, v25, v25
	v_fmac_f32_e32 v9, v26, v26
	v_fmac_f32_e32 v11, v27, v27
	ds_read_b128 v[12:15], v10 offset:192
	ds_read_b128 v[16:19], v10 offset:208
	ds_read_b128 v[20:23], v10 offset:224
	ds_read_b128 v[24:27], v10 offset:240
	s_waitcnt lgkmcnt(3)
	v_fmac_f32_e32 v7, v12, v12
	v_fmac_f32_e32 v8, v13, v13
	v_fmac_f32_e32 v9, v14, v14
	v_fmac_f32_e32 v11, v15, v15
	s_waitcnt lgkmcnt(2)
	v_fmac_f32_e32 v7, v16, v16
	v_fmac_f32_e32 v8, v17, v17
	v_fmac_f32_e32 v9, v18, v18
	v_fmac_f32_e32 v11, v19, v19
	s_waitcnt lgkmcnt(1)
	v_fmac_f32_e32 v7, v20, v20
	v_fmac_f32_e32 v8, v21, v21
	v_fmac_f32_e32 v9, v22, v22
	v_fmac_f32_e32 v11, v23, v23
	s_waitcnt lgkmcnt(0)
	v_fmac_f32_e32 v7, v24, v24
	v_fmac_f32_e32 v8, v25, v25
	v_fmac_f32_e32 v9, v26, v26
	v_fmac_f32_e32 v11, v27, v27
	v_add_f32_e32 v7, v7, v8
	v_add_f32_e32 v9, v9, v11
	v_add_f32_e32 v7, v7, v9
	ds_bpermute_b32 v4, v130, v7
	v_mov_b32_e32 v5, 0x3727c5ac
	v_lshlrev_b32_e32 v160, 2, v6
	v_lshl_add_u64 v[2:3], v[2:3], 0, s[56:57]
	s_waitcnt lgkmcnt(0)
	v_add_f32_e32 v4, v7, v4
	v_fmamk_f32 v4, v4, 0x3c000000, v5
	v_mul_f32_e32 v5, 0x4f800000, v4
	v_cmp_gt_f32_e32 vcc, s3, v4
	s_nop 1
	v_cndmask_b32_e32 v4, v4, v5, vcc
	v_sqrt_f32_e32 v5, v4
	s_nop 0
	v_add_u32_e32 v7, -1, v5
	v_add_u32_e32 v8, 1, v5
	v_fma_f32 v9, -v7, v5, v4
	v_fma_f32 v11, -v8, v5, v4
	v_cmp_ge_f32_e64 s[0:1], 0, v9
	s_nop 1
	v_cndmask_b32_e64 v5, v5, v7, s[0:1]
	v_cmp_lt_f32_e64 s[0:1], 0, v11
	s_nop 1
	v_cndmask_b32_e64 v5, v5, v8, s[0:1]
	v_mul_f32_e32 v7, 0x37800000, v5
	v_cndmask_b32_e32 v5, v5, v7, vcc
	v_cmp_class_f32_e32 vcc, v4, v188
	s_nop 1
	v_cndmask_b32_e32 v4, v5, v4, vcc
	v_div_scale_f32 v5, s[0:1], v4, v4, v191
	v_rcp_f32_e32 v7, v5
	s_add_u32 s0, s9, s22
	s_addc_u32 s1, s8, s23
	v_fma_f32 v8, -v5, v7, 1.0
	v_fmac_f32_e32 v7, v8, v7
	v_div_scale_f32 v8, vcc, v191, v4, v191
	v_mul_f32_e32 v9, v8, v7
	v_fma_f32 v11, -v5, v9, v8
	v_fmac_f32_e32 v9, v11, v7
	v_fma_f32 v5, -v5, v9, v8
	v_div_fmas_f32 v5, v5, v7, v9
	v_lshl_add_u64 v[6:7], s[0:1], 0, v[160:161]
	v_lshlrev_b32_e32 v160, 7, v66
	v_div_fixup_f32 v4, v5, v4, v191
	v_lshl_add_u64 v[2:3], v[2:3], 0, v[160:161]
	v_mov_b32_e32 v5, v4
	v_mov_b32_e32 v8, v4
	v_mov_b32_e32 v9, v4
	v_lshl_add_u64 v[2:3], s[20:21], 0, v[2:3]
	v_mov_b32_e32 v252, v10
	s_mov_b64 s[0:1], 0
